# v64 + P9 K-loops: the 48 per-burst s_setprio flips removed; all MFMA bursts placed at byte phase 4 mod 8
# baseline (speedup 1.0000x reference)
; #define PG8_STAGE(bufoff, gbase, voff) do { _Pragma("unroll") for (int _i = 0; _i < 2; ++_i) \
;         __builtin_amdgcn_global_load_lds((const unsigned*)((const char*)(gbase) + (voff)[_i]), (PG8_LAS unsigned*)(lds + (bufoff) + ldsw + _i * 8192), 16, 0, 0); } while (0)
; #define PG8_STAGE_NT(bufoff, gbase, voff) do { _Pragma("unroll") for (int _i = 0; _i < 2; ++_i) \
;         __builtin_amdgcn_global_load_lds((const unsigned*)((const char*)(gbase) + (voff)[_i]), (PG8_LAS unsigned*)(lds + (bufoff) + ldsw + _i * 8192), 16, 0, PG8_B_AUX); } while (0)
; #define PG8_LDA(dst, b, h) do { _Pragma("unroll") for (int m = 0; m < 4; ++m) _Pragma("unroll") for (int k = 0; k < 2; ++k) dst[m][k] = *(const PG8_LAS bf16x8*)(lds + PG8_SA(b, h) + aoff + m * 2048 + k * 1024); } while (0)
; #define PG8_LDB(dst, b, h) do { _Pragma("unroll") for (int n = 0; n < 2; ++n) _Pragma("unroll") for (int k = 0; k < 2; ++k) dst[n][k] = *(const PG8_LAS bf16x8*)(lds + PG8_SB(b, h) + boff + n * 2048 + k * 1024); } while (0)
; #define PG8_WAIT_V(n) asm volatile("s_waitcnt vmcnt(" #n ")" ::: "memory")
; #define PG8_WAIT_L(n) asm volatile("s_waitcnt lgkmcnt(" #n ")" ::: "memory")
; #define PG8_BAR __builtin_amdgcn_s_barrier()
; #define PG8_SCHED __builtin_amdgcn_sched_barrier(0)
; template <class Epi, class Sched, bool ALIGN_EPI = false, bool SP2 = false>
; __device__ __forceinline__ void gemm_phase(PG8_LAS unsigned char* lds, const Gemm g, const Sched& S, const Epi& E, int wid) {
;     ...
;             const bool last = (t == nt - 2);
;             const char* a1 = cA + (size_t)(t + 1) * kstep;
;             const char* a2 = last ? nA : cA + (size_t)(t + 2) * kstep; const char* b2 = last ? nB : cB + (size_t)(t + 2) * kstep;
;             const char* a3 = a2 + kstep; const char* b3 = b2 + kstep;
;             if (last && has_next) S.a_ready(nxt);
;             if constexpr (SP2) {
;             PG8_LDB(B0, 0, 0); PG8_LDB(B1, 0, 1); PG8_SCHED; PG8_LDA(At, 0, 0); PG8_STAGE(PG8_SA(1, 1), a1 + hstepA, voffA);
;             PG8_WAIT_V(8); PG8_WAIT_L(0); PG8_BAR; PG8_MMA(0, 0, At, B0); PG8_MMA(0, 1, At, B1); PG8_BAR; PG8_SCHED;
;             PG8_LDA(At, 0, 1); PG8_STAGE_NT(PG8_SB(0, 0), b2, voffB); PG8_STAGE_NT(PG8_SB(0, 1), b2 + hstepB, voffB); PG8_STAGE(PG8_SA(0, 0), a2, voffA);
;             PG8_WAIT_V(8); PG8_WAIT_L(0); PG8_BAR; PG8_MMA(1, 0, At, B0); PG8_MMA(1, 1, At, B1); PG8_BAR; PG8_SCHED;
.LBB0_1221:
	ds_read_b128 v[128:131], v205
	ds_read_b128 v[132:135], v205 offset:1024
	ds_read_b128 v[136:139], v205 offset:2048
	ds_read_b128 v[140:143], v205 offset:3072
	ds_read_b128 v[144:147], v206
	ds_read_b128 v[148:151], v206 offset:1024
	ds_read_b128 v[152:155], v206 offset:2048
	ds_read_b128 v[156:159], v206 offset:3072
	s_add_u32 s48, s46, 0x100
	s_addc_u32 s49, s47, 0
	s_cmpk_eq_i32 s63, 0xa8
	s_cselect_b32 s53, s7, s49
	s_cselect_b32 s52, s6, s48
	s_cselect_b32 s51, s45, s62
	s_cselect_b32 s50, s44, s61
	v_lshl_add_u64 v[200:201], s[46:47], 0, v[176:177]
	s_add_i32 m0, s17, 0xc000
	ds_read_b128 v[160:163], v207
	ds_read_b128 v[164:167], v207 offset:1024
	ds_read_b128 v[184:187], v207 offset:2048
	ds_read_b128 v[188:191], v207 offset:3072
	ds_read_b128 v[192:195], v207 offset:4096
	ds_read_b128 v[196:199], v207 offset:5120
	ds_read_b128 v[210:213], v207 offset:6144
	ds_read_b128 v[214:217], v207 offset:7168
	global_load_lds_dwordx4 v[200:201], off
	v_lshl_add_u64 v[200:201], s[46:47], 0, v[178:179]
	s_add_i32 m0, s17, 0xe000
	s_nop 0
	global_load_lds_dwordx4 v[200:201], off
	s_nop 0
	s_waitcnt vmcnt(8)
	s_waitcnt lgkmcnt(0)
	s_barrier
	s_waitcnt lgkmcnt(0)
	v_mfma_f32_16x16x32_bf16 v[124:127], v[128:131], v[160:163], v[124:127]
	v_mfma_f32_16x16x32_bf16 v[120:123], v[136:139], v[160:163], v[120:123]
	v_mfma_f32_16x16x32_bf16 v[116:119], v[128:131], v[184:187], v[116:119]
	v_mfma_f32_16x16x32_bf16 v[112:115], v[136:139], v[184:187], v[112:115]
	v_mfma_f32_16x16x32_bf16 v[92:95], v[128:131], v[192:195], v[92:95]
	v_mfma_f32_16x16x32_bf16 v[88:91], v[136:139], v[192:195], v[88:91]
	v_mfma_f32_16x16x32_bf16 v[76:79], v[128:131], v[210:213], v[76:79]
	v_mfma_f32_16x16x32_bf16 v[72:75], v[136:139], v[210:213], v[72:75]
	v_mfma_f32_16x16x32_bf16 v[124:127], v[132:135], v[164:167], v[124:127]
	v_mfma_f32_16x16x32_bf16 v[120:123], v[140:143], v[164:167], v[120:123]
	v_mfma_f32_16x16x32_bf16 v[116:119], v[132:135], v[188:191], v[116:119]
	v_mfma_f32_16x16x32_bf16 v[112:115], v[140:143], v[188:191], v[112:115]
	v_mfma_f32_16x16x32_bf16 v[92:95], v[132:135], v[196:199], v[92:95]
	v_mfma_f32_16x16x32_bf16 v[88:91], v[140:143], v[196:199], v[88:91]
	v_mfma_f32_16x16x32_bf16 v[76:79], v[132:135], v[214:217], v[76:79]
	v_mfma_f32_16x16x32_bf16 v[72:75], v[140:143], v[214:217], v[72:75]
	v_mfma_f32_16x16x32_bf16 v[108:111], v[144:147], v[160:163], v[108:111]
	v_mfma_f32_16x16x32_bf16 v[104:107], v[152:155], v[160:163], v[104:107]
	v_mfma_f32_16x16x32_bf16 v[100:103], v[144:147], v[184:187], v[100:103]
	v_mfma_f32_16x16x32_bf16 v[96:99], v[152:155], v[184:187], v[96:99]
	v_mfma_f32_16x16x32_bf16 v[84:87], v[144:147], v[192:195], v[84:87]
	v_mfma_f32_16x16x32_bf16 v[80:83], v[152:155], v[192:195], v[80:83]
	v_mfma_f32_16x16x32_bf16 v[68:71], v[144:147], v[210:213], v[68:71]
	v_mfma_f32_16x16x32_bf16 v[64:67], v[152:155], v[210:213], v[64:67]
	v_mfma_f32_16x16x32_bf16 v[108:111], v[148:151], v[164:167], v[108:111]
	v_mfma_f32_16x16x32_bf16 v[104:107], v[156:159], v[164:167], v[104:107]
	v_mfma_f32_16x16x32_bf16 v[100:103], v[148:151], v[188:191], v[100:103]
	v_mfma_f32_16x16x32_bf16 v[96:99], v[156:159], v[188:191], v[96:99]
	v_mfma_f32_16x16x32_bf16 v[84:87], v[148:151], v[196:199], v[84:87]
	v_mfma_f32_16x16x32_bf16 v[80:83], v[156:159], v[196:199], v[80:83]
	v_mfma_f32_16x16x32_bf16 v[68:71], v[148:151], v[214:217], v[68:71]
	v_mfma_f32_16x16x32_bf16 v[64:67], v[156:159], v[214:217], v[64:67]
	s_barrier
	s_add_i32 s46, s56, s9
	v_lshl_add_u64 v[200:201], s[50:51], 0, v[170:171]
	s_mov_b32 m0, s46
	ds_read_b128 v[160:163], v207 offset:16384
	ds_read_b128 v[164:167], v207 offset:17408
	ds_read_b128 v[184:187], v207 offset:18432
	ds_read_b128 v[188:191], v207 offset:19456
	ds_read_b128 v[192:195], v207 offset:20480
	ds_read_b128 v[196:199], v207 offset:21504
	ds_read_b128 v[210:213], v207 offset:22528
	ds_read_b128 v[214:217], v207 offset:23552
	global_load_lds_dwordx4 v[200:201], off
	s_add_i32 m0, s46, 0x2000
	s_add_u32 s46, s50, 0x2b4000
	v_lshl_add_u64 v[218:219], s[50:51], 0, v[174:175]
	s_addc_u32 s47, s51, 0
	s_add_i32 s64, s57, s9
	global_load_lds_dwordx4 v[218:219], off
	v_lshl_add_u64 v[220:221], s[46:47], 0, v[170:171]
	s_mov_b32 m0, s64
	v_lshl_add_u64 v[222:223], s[52:53], 0, v[172:173]
	global_load_lds_dwordx4 v[220:221], off
	v_lshl_add_u64 v[220:221], s[46:47], 0, v[174:175]
	s_add_i32 m0, s64, 0x2000
	s_nop 0
	global_load_lds_dwordx4 v[220:221], off
	v_lshl_add_u64 v[220:221], s[52:53], 0, v[168:169]
	s_mov_b32 m0, s17
	s_nop 0
	global_load_lds_dwordx4 v[220:221], off
	s_mov_b32 m0, s19
	s_nop 0
	global_load_lds_dwordx4 v[222:223], off
	s_nop 0
	s_waitcnt vmcnt(8)
	s_waitcnt lgkmcnt(0)
	s_barrier
; #define PG8_STAGE(bufoff, gbase, voff) do { _Pragma("unroll") for (int _i = 0; _i < 2; ++_i) \
;         __builtin_amdgcn_global_load_lds((const unsigned*)((const char*)(gbase) + (voff)[_i]), (PG8_LAS unsigned*)(lds + (bufoff) + ldsw + _i * 8192), 16, 0, 0); } while (0)
; #define PG8_STAGE_NT(bufoff, gbase, voff) do { _Pragma("unroll") for (int _i = 0; _i < 2; ++_i) \
;         __builtin_amdgcn_global_load_lds((const unsigned*)((const char*)(gbase) + (voff)[_i]), (PG8_LAS unsigned*)(lds + (bufoff) + ldsw + _i * 8192), 16, 0, PG8_B_AUX); } while (0)
; #define PG8_LDA(dst, b, h) do { _Pragma("unroll") for (int m = 0; m < 4; ++m) _Pragma("unroll") for (int k = 0; k < 2; ++k) dst[m][k] = *(const PG8_LAS bf16x8*)(lds + PG8_SA(b, h) + aoff + m * 2048 + k * 1024); } while (0)
; #define PG8_LDB(dst, b, h) do { _Pragma("unroll") for (int n = 0; n < 2; ++n) _Pragma("unroll") for (int k = 0; k < 2; ++k) dst[n][k] = *(const PG8_LAS bf16x8*)(lds + PG8_SB(b, h) + boff + n * 2048 + k * 1024); } while (0)
; #define PG8_MMA(ai, bj, At, Bt) do { __builtin_amdgcn_s_setprio(1); _Pragma("unroll") for (int m = 0; m < 4; ++m) _Pragma("unroll") for (int n = 0; n < 2; ++n) _Pragma("unroll") for (int k = 0; k < 2; ++k) \
;         acc[ai][bj][m][n] = __builtin_amdgcn_mfma_f32_16x16x32_bf16(Bt[n][k], At[m][k], acc[ai][bj][m][n], 0, 0, 0); __builtin_amdgcn_s_setprio(0); } while (0)
; #define PG8_WAIT_V(n) asm volatile("s_waitcnt vmcnt(" #n ")" ::: "memory")
; #define PG8_WAIT_L(n) asm volatile("s_waitcnt lgkmcnt(" #n ")" ::: "memory")
; template <class Epi, class Sched, bool ALIGN_EPI = false, bool SP2 = false>
; __device__ __forceinline__ void gemm_phase(PG8_LAS unsigned char* lds, const Gemm g, const Sched& S, const Epi& E, int wid) {
;     ...
;             PG8_WAIT_V(8); PG8_WAIT_L(0); PG8_BAR; PG8_MMA(0, 0, At, B0); PG8_MMA(0, 1, At, B1); PG8_BAR; PG8_SCHED;
;             PG8_LDA(At, 0, 1); PG8_STAGE_NT(PG8_SB(0, 0), b2, voffB); PG8_STAGE_NT(PG8_SB(0, 1), b2 + hstepB, voffB); PG8_STAGE(PG8_SA(0, 0), a2, voffA);
;             PG8_WAIT_V(8); PG8_WAIT_L(0); PG8_BAR; PG8_MMA(1, 0, At, B0); PG8_MMA(1, 1, At, B1); PG8_BAR; PG8_SCHED;
;             PG8_LDB(B0, 1, 0); PG8_LDB(B1, 1, 1); PG8_SCHED; PG8_LDA(At, 1, 0); PG8_STAGE(PG8_SA(0, 1), a2 + hstepA, voffA);
;             PG8_WAIT_V(8); PG8_WAIT_L(0); PG8_BAR; PG8_MMA(0, 0, At, B0); PG8_MMA(0, 1, At, B1); PG8_BAR; PG8_SCHED;
	s_waitcnt lgkmcnt(0)
	v_mfma_f32_16x16x32_bf16 v[60:63], v[128:131], v[160:163], v[60:63]
	v_mfma_f32_16x16x32_bf16 v[56:59], v[136:139], v[160:163], v[56:59]
	v_mfma_f32_16x16x32_bf16 v[44:47], v[128:131], v[184:187], v[44:47]
	v_mfma_f32_16x16x32_bf16 v[40:43], v[136:139], v[184:187], v[40:43]
	v_mfma_f32_16x16x32_bf16 v[28:31], v[128:131], v[192:195], v[28:31]
	v_mfma_f32_16x16x32_bf16 v[24:27], v[136:139], v[192:195], v[24:27]
	v_mfma_f32_16x16x32_bf16 v[12:15], v[128:131], v[210:213], v[12:15]
	v_mfma_f32_16x16x32_bf16 v[8:11], v[136:139], v[210:213], v[8:11]
	v_mfma_f32_16x16x32_bf16 v[60:63], v[132:135], v[164:167], v[60:63]
	v_mfma_f32_16x16x32_bf16 v[56:59], v[140:143], v[164:167], v[56:59]
	v_mfma_f32_16x16x32_bf16 v[44:47], v[132:135], v[188:191], v[44:47]
	v_mfma_f32_16x16x32_bf16 v[40:43], v[140:143], v[188:191], v[40:43]
	v_mfma_f32_16x16x32_bf16 v[28:31], v[132:135], v[196:199], v[28:31]
	v_mfma_f32_16x16x32_bf16 v[24:27], v[140:143], v[196:199], v[24:27]
	v_mfma_f32_16x16x32_bf16 v[12:15], v[132:135], v[214:217], v[12:15]
	v_mfma_f32_16x16x32_bf16 v[8:11], v[140:143], v[214:217], v[8:11]
	v_mfma_f32_16x16x32_bf16 v[52:55], v[144:147], v[160:163], v[52:55]
	v_mfma_f32_16x16x32_bf16 v[48:51], v[152:155], v[160:163], v[48:51]
	v_mfma_f32_16x16x32_bf16 v[36:39], v[144:147], v[184:187], v[36:39]
	v_mfma_f32_16x16x32_bf16 v[32:35], v[152:155], v[184:187], v[32:35]
	v_mfma_f32_16x16x32_bf16 v[20:23], v[144:147], v[192:195], v[20:23]
	v_mfma_f32_16x16x32_bf16 v[16:19], v[152:155], v[192:195], v[16:19]
	v_mfma_f32_16x16x32_bf16 v[4:7], v[144:147], v[210:213], v[4:7]
	v_mfma_f32_16x16x32_bf16 v[0:3], v[152:155], v[210:213], v[0:3]
	v_mfma_f32_16x16x32_bf16 v[52:55], v[148:151], v[164:167], v[52:55]
	v_mfma_f32_16x16x32_bf16 v[48:51], v[156:159], v[164:167], v[48:51]
	v_mfma_f32_16x16x32_bf16 v[36:39], v[148:151], v[188:191], v[36:39]
	v_mfma_f32_16x16x32_bf16 v[32:35], v[156:159], v[188:191], v[32:35]
	v_mfma_f32_16x16x32_bf16 v[20:23], v[148:151], v[196:199], v[20:23]
	v_mfma_f32_16x16x32_bf16 v[16:19], v[156:159], v[196:199], v[16:19]
	v_mfma_f32_16x16x32_bf16 v[4:7], v[148:151], v[214:217], v[4:7]
	v_mfma_f32_16x16x32_bf16 v[0:3], v[156:159], v[214:217], v[0:3]
	s_barrier
	s_add_i32 s64, 0, 0x18000
	s_add_i32 s65, 0, 0x1c000
	v_add_u32_e32 v140, s64, v203
	v_add_u32_e32 v156, s65, v203
	ds_read_b128 v[128:131], v140
	ds_read_b128 v[132:135], v140 offset:1024
	ds_read_b128 v[136:139], v140 offset:2048
	ds_read_b128 v[140:143], v140 offset:3072
	ds_read_b128 v[144:147], v156
	ds_read_b128 v[148:151], v156 offset:1024
	ds_read_b128 v[152:155], v156 offset:2048
	ds_read_b128 v[156:159], v156 offset:3072
	s_add_u32 s46, s52, 0x2b4000
	s_addc_u32 s47, s53, 0
	s_mov_b32 m0, s22
	v_lshl_add_u64 v[224:225], s[46:47], 0, v[168:169]
	ds_read_b128 v[160:163], v207 offset:32768
	ds_read_b128 v[164:167], v207 offset:33792
	ds_read_b128 v[184:187], v207 offset:34816
	ds_read_b128 v[188:191], v207 offset:35840
	ds_read_b128 v[192:195], v207 offset:36864
	ds_read_b128 v[196:199], v207 offset:37888
	ds_read_b128 v[210:213], v207 offset:38912
	ds_read_b128 v[214:217], v207 offset:39936
	global_load_lds_dwordx4 v[224:225], off
	v_lshl_add_u64 v[224:225], s[46:47], 0, v[172:173]
	s_mov_b32 m0, s23
	s_nop 0
	global_load_lds_dwordx4 v[224:225], off
	s_nop 0
	s_waitcnt vmcnt(8)
	s_waitcnt lgkmcnt(0)
	s_barrier
	s_waitcnt lgkmcnt(0)
	v_mfma_f32_16x16x32_bf16 v[124:127], v[128:131], v[160:163], v[124:127]
	v_mfma_f32_16x16x32_bf16 v[120:123], v[136:139], v[160:163], v[120:123]
	v_mfma_f32_16x16x32_bf16 v[116:119], v[128:131], v[184:187], v[116:119]
	v_mfma_f32_16x16x32_bf16 v[112:115], v[136:139], v[184:187], v[112:115]
	v_mfma_f32_16x16x32_bf16 v[92:95], v[128:131], v[192:195], v[92:95]
	v_mfma_f32_16x16x32_bf16 v[88:91], v[136:139], v[192:195], v[88:91]
	v_mfma_f32_16x16x32_bf16 v[76:79], v[128:131], v[210:213], v[76:79]
	v_mfma_f32_16x16x32_bf16 v[72:75], v[136:139], v[210:213], v[72:75]
	v_mfma_f32_16x16x32_bf16 v[124:127], v[132:135], v[164:167], v[124:127]
	v_mfma_f32_16x16x32_bf16 v[120:123], v[140:143], v[164:167], v[120:123]
	v_mfma_f32_16x16x32_bf16 v[116:119], v[132:135], v[188:191], v[116:119]
	v_mfma_f32_16x16x32_bf16 v[112:115], v[140:143], v[188:191], v[112:115]
	v_mfma_f32_16x16x32_bf16 v[92:95], v[132:135], v[196:199], v[92:95]
	v_mfma_f32_16x16x32_bf16 v[88:91], v[140:143], v[196:199], v[88:91]
	v_mfma_f32_16x16x32_bf16 v[76:79], v[132:135], v[214:217], v[76:79]
	v_mfma_f32_16x16x32_bf16 v[72:75], v[140:143], v[214:217], v[72:75]
	v_mfma_f32_16x16x32_bf16 v[108:111], v[144:147], v[160:163], v[108:111]
	v_mfma_f32_16x16x32_bf16 v[104:107], v[152:155], v[160:163], v[104:107]
	v_mfma_f32_16x16x32_bf16 v[100:103], v[144:147], v[184:187], v[100:103]
	v_mfma_f32_16x16x32_bf16 v[96:99], v[152:155], v[184:187], v[96:99]
	v_mfma_f32_16x16x32_bf16 v[84:87], v[144:147], v[192:195], v[84:87]
	v_mfma_f32_16x16x32_bf16 v[80:83], v[152:155], v[192:195], v[80:83]
	v_mfma_f32_16x16x32_bf16 v[68:71], v[144:147], v[210:213], v[68:71]
	v_mfma_f32_16x16x32_bf16 v[64:67], v[152:155], v[210:213], v[64:67]
	v_mfma_f32_16x16x32_bf16 v[108:111], v[148:151], v[164:167], v[108:111]
	v_mfma_f32_16x16x32_bf16 v[104:107], v[156:159], v[164:167], v[104:107]
	v_mfma_f32_16x16x32_bf16 v[100:103], v[148:151], v[188:191], v[100:103]
	v_mfma_f32_16x16x32_bf16 v[96:99], v[156:159], v[188:191], v[96:99]
	v_mfma_f32_16x16x32_bf16 v[84:87], v[148:151], v[196:199], v[84:87]
	v_mfma_f32_16x16x32_bf16 v[80:83], v[156:159], v[196:199], v[80:83]
	v_mfma_f32_16x16x32_bf16 v[68:71], v[148:151], v[214:217], v[68:71]
	v_mfma_f32_16x16x32_bf16 v[64:67], v[156:159], v[214:217], v[64:67]
	s_barrier
; #define PG8_STAGE(bufoff, gbase, voff) do { _Pragma("unroll") for (int _i = 0; _i < 2; ++_i) \
;         __builtin_amdgcn_global_load_lds((const unsigned*)((const char*)(gbase) + (voff)[_i]), (PG8_LAS unsigned*)(lds + (bufoff) + ldsw + _i * 8192), 16, 0, 0); } while (0)
; #define PG8_STAGE_NT(bufoff, gbase, voff) do { _Pragma("unroll") for (int _i = 0; _i < 2; ++_i) \
;         __builtin_amdgcn_global_load_lds((const unsigned*)((const char*)(gbase) + (voff)[_i]), (PG8_LAS unsigned*)(lds + (bufoff) + ldsw + _i * 8192), 16, 0, PG8_B_AUX); } while (0)
; #define PG8_LDA(dst, b, h) do { _Pragma("unroll") for (int m = 0; m < 4; ++m) _Pragma("unroll") for (int k = 0; k < 2; ++k) dst[m][k] = *(const PG8_LAS bf16x8*)(lds + PG8_SA(b, h) + aoff + m * 2048 + k * 1024); } while (0)
; #define PG8_MMA(ai, bj, At, Bt) do { __builtin_amdgcn_s_setprio(1); _Pragma("unroll") for (int m = 0; m < 4; ++m) _Pragma("unroll") for (int n = 0; n < 2; ++n) _Pragma("unroll") for (int k = 0; k < 2; ++k) \
;         acc[ai][bj][m][n] = __builtin_amdgcn_mfma_f32_16x16x32_bf16(Bt[n][k], At[m][k], acc[ai][bj][m][n], 0, 0, 0); __builtin_amdgcn_s_setprio(0); } while (0)
; #define PG8_WAIT_V(n) asm volatile("s_waitcnt vmcnt(" #n ")" ::: "memory")
; #define PG8_WAIT_L(n) asm volatile("s_waitcnt lgkmcnt(" #n ")" ::: "memory")
; #define PG8_BAR __builtin_amdgcn_s_barrier()
; #define PG8_SCHED __builtin_amdgcn_sched_barrier(0)
; template <class Epi, class Sched, bool ALIGN_EPI = false, bool SP2 = false>
; __device__ __forceinline__ void gemm_phase(PG8_LAS unsigned char* lds, const Gemm g, const Sched& S, const Epi& E, int wid) {
;     ...
;             PG8_LDA(At, 1, 1); PG8_STAGE_NT(PG8_SB(1, 0), b3, voffB); PG8_STAGE_NT(PG8_SB(1, 1), b3 + hstepB, voffB); PG8_STAGE(PG8_SA(1, 0), a3, voffA);
;             PG8_WAIT_V(8); PG8_WAIT_L(0); PG8_BAR; PG8_MMA(1, 0, At, B0); PG8_MMA(1, 1, At, B1); PG8_BAR; PG8_SCHED;
;     ...
;         if constexpr (ALIGN_EPI) { if (wr == 0) PG8_BAR; }
	s_add_i32 s46, s64, s9
	v_lshl_add_u64 v[200:201], v[200:201], 0, s[40:41]
	s_mov_b32 m0, s46
	ds_read_b128 v[160:163], v207 offset:49152
	ds_read_b128 v[164:167], v207 offset:50176
	ds_read_b128 v[184:187], v207 offset:51200
	ds_read_b128 v[188:191], v207 offset:52224
	ds_read_b128 v[192:195], v207 offset:53248
	ds_read_b128 v[196:199], v207 offset:54272
	ds_read_b128 v[210:213], v207 offset:55296
	ds_read_b128 v[214:217], v207 offset:56320
	global_load_lds_dwordx4 v[200:201], off
	s_add_i32 m0, s46, 0x2000
	s_add_u32 s46, s50, 0x2b4080
	v_lshl_add_u64 v[200:201], v[218:219], 0, s[40:41]
	s_addc_u32 s47, s51, 0
	s_add_i32 s50, s65, s9
	global_load_lds_dwordx4 v[200:201], off
	v_lshl_add_u64 v[200:201], s[46:47], 0, v[170:171]
	s_mov_b32 m0, s50
	s_nop 0
	global_load_lds_dwordx4 v[200:201], off
	v_lshl_add_u64 v[200:201], s[46:47], 0, v[174:175]
	s_add_i32 m0, s50, 0x2000
	s_nop 0
	global_load_lds_dwordx4 v[200:201], off
	v_lshl_add_u64 v[200:201], v[220:221], 0, s[40:41]
	s_mov_b32 m0, s25
	s_nop 0
	global_load_lds_dwordx4 v[200:201], off
	v_lshl_add_u64 v[200:201], v[222:223], 0, s[40:41]
	s_mov_b32 m0, s29
	s_nop 0
	global_load_lds_dwordx4 v[200:201], off
	s_waitcnt vmcnt(8)
	s_waitcnt lgkmcnt(0)
	s_barrier
	s_waitcnt lgkmcnt(0)
	v_mfma_f32_16x16x32_bf16 v[60:63], v[128:131], v[160:163], v[60:63]
	v_mfma_f32_16x16x32_bf16 v[56:59], v[136:139], v[160:163], v[56:59]
	v_mfma_f32_16x16x32_bf16 v[44:47], v[128:131], v[184:187], v[44:47]
	v_mfma_f32_16x16x32_bf16 v[40:43], v[136:139], v[184:187], v[40:43]
	v_mfma_f32_16x16x32_bf16 v[28:31], v[128:131], v[192:195], v[28:31]
	v_mfma_f32_16x16x32_bf16 v[24:27], v[136:139], v[192:195], v[24:27]
	v_mfma_f32_16x16x32_bf16 v[12:15], v[128:131], v[210:213], v[12:15]
	v_mfma_f32_16x16x32_bf16 v[8:11], v[136:139], v[210:213], v[8:11]
	v_mfma_f32_16x16x32_bf16 v[60:63], v[132:135], v[164:167], v[60:63]
	v_mfma_f32_16x16x32_bf16 v[56:59], v[140:143], v[164:167], v[56:59]
	v_mfma_f32_16x16x32_bf16 v[44:47], v[132:135], v[188:191], v[44:47]
	v_mfma_f32_16x16x32_bf16 v[40:43], v[140:143], v[188:191], v[40:43]
	v_mfma_f32_16x16x32_bf16 v[28:31], v[132:135], v[196:199], v[28:31]
	v_mfma_f32_16x16x32_bf16 v[24:27], v[140:143], v[196:199], v[24:27]
	v_mfma_f32_16x16x32_bf16 v[12:15], v[132:135], v[214:217], v[12:15]
	v_mfma_f32_16x16x32_bf16 v[8:11], v[140:143], v[214:217], v[8:11]
	v_mfma_f32_16x16x32_bf16 v[52:55], v[144:147], v[160:163], v[52:55]
	v_mfma_f32_16x16x32_bf16 v[48:51], v[152:155], v[160:163], v[48:51]
	v_mfma_f32_16x16x32_bf16 v[36:39], v[144:147], v[184:187], v[36:39]
	v_mfma_f32_16x16x32_bf16 v[32:35], v[152:155], v[184:187], v[32:35]
	v_mfma_f32_16x16x32_bf16 v[20:23], v[144:147], v[192:195], v[20:23]
	v_mfma_f32_16x16x32_bf16 v[16:19], v[152:155], v[192:195], v[16:19]
	v_mfma_f32_16x16x32_bf16 v[4:7], v[144:147], v[210:213], v[4:7]
	v_mfma_f32_16x16x32_bf16 v[0:3], v[152:155], v[210:213], v[0:3]
	v_mfma_f32_16x16x32_bf16 v[52:55], v[148:151], v[164:167], v[52:55]
	v_mfma_f32_16x16x32_bf16 v[48:51], v[156:159], v[164:167], v[48:51]
	v_mfma_f32_16x16x32_bf16 v[36:39], v[148:151], v[188:191], v[36:39]
	v_mfma_f32_16x16x32_bf16 v[32:35], v[156:159], v[188:191], v[32:35]
	v_mfma_f32_16x16x32_bf16 v[20:23], v[148:151], v[196:199], v[20:23]
	v_mfma_f32_16x16x32_bf16 v[16:19], v[156:159], v[196:199], v[16:19]
	v_mfma_f32_16x16x32_bf16 v[4:7], v[148:151], v[214:217], v[4:7]
	v_mfma_f32_16x16x32_bf16 v[0:3], v[156:159], v[214:217], v[0:3]
	s_barrier
	s_add_i32 s63, s63, 2
	s_add_u32 s61, s61, 0x100
	s_addc_u32 s62, s62, 0
	s_cmpk_gt_u32 s63, 0xa9
	s_mov_b64 s[46:47], s[48:49]
	s_cbranch_scc0 .LBB0_1221
	s_and_b64 vcc, exec, s[42:43]
	s_cbranch_vccz .LBB0_1224
	s_barrier

; #define PG8_STAGE(bufoff, gbase, voff) do { _Pragma("unroll") for (int _i = 0; _i < 2; ++_i) \
;         __builtin_amdgcn_global_load_lds((const unsigned*)((const char*)(gbase) + (voff)[_i]), (PG8_LAS unsigned*)(lds + (bufoff) + ldsw + _i * 8192), 16, 0, 0); } while (0)
; #define PG8_STAGE_NT(bufoff, gbase, voff) do { _Pragma("unroll") for (int _i = 0; _i < 2; ++_i) \
;         __builtin_amdgcn_global_load_lds((const unsigned*)((const char*)(gbase) + (voff)[_i]), (PG8_LAS unsigned*)(lds + (bufoff) + ldsw + _i * 8192), 16, 0, PG8_B_AUX); } while (0)
; #define PG8_LDA(dst, b, h) do { _Pragma("unroll") for (int m = 0; m < 4; ++m) _Pragma("unroll") for (int k = 0; k < 2; ++k) dst[m][k] = *(const PG8_LAS bf16x8*)(lds + PG8_SA(b, h) + aoff + m * 2048 + k * 1024); } while (0)
; #define PG8_LDB(dst, b, h) do { _Pragma("unroll") for (int n = 0; n < 2; ++n) _Pragma("unroll") for (int k = 0; k < 2; ++k) dst[n][k] = *(const PG8_LAS bf16x8*)(lds + PG8_SB(b, h) + boff + n * 2048 + k * 1024); } while (0)
; #define PG8_WAIT_V(n) asm volatile("s_waitcnt vmcnt(" #n ")" ::: "memory")
; #define PG8_WAIT_L(n) asm volatile("s_waitcnt lgkmcnt(" #n ")" ::: "memory")
; #define PG8_BAR __builtin_amdgcn_s_barrier()
; #define PG8_SCHED __builtin_amdgcn_sched_barrier(0)
; template <class Epi, class Sched, bool ALIGN_EPI = false, bool SP2 = false>
; __device__ __forceinline__ void gemm_phase(PG8_LAS unsigned char* lds, const Gemm g, const Sched& S, const Epi& E, int wid) {
;     ...
;             const bool last = (t == nt - 2);
;             const char* a1 = cA + (size_t)(t + 1) * kstep;
;             const char* a2 = last ? nA : cA + (size_t)(t + 2) * kstep; const char* b2 = last ? nB : cB + (size_t)(t + 2) * kstep;
;             const char* a3 = a2 + kstep; const char* b3 = b2 + kstep;
;             if (last && has_next) S.a_ready(nxt);
;             if constexpr (SP2) {
;             PG8_LDB(B0, 0, 0); PG8_LDB(B1, 0, 1); PG8_SCHED; PG8_LDA(At, 0, 0); PG8_STAGE(PG8_SA(1, 1), a1 + hstepA, voffA);
;             PG8_WAIT_V(8); PG8_WAIT_L(0); PG8_BAR; PG8_MMA(0, 0, At, B0); PG8_MMA(0, 1, At, B1); PG8_BAR; PG8_SCHED;
;             PG8_LDA(At, 0, 1); PG8_STAGE_NT(PG8_SB(0, 0), b2, voffB); PG8_STAGE_NT(PG8_SB(0, 1), b2 + hstepB, voffB); PG8_STAGE(PG8_SA(0, 0), a2, voffA);
;             PG8_WAIT_V(8); PG8_WAIT_L(0); PG8_BAR; PG8_MMA(1, 0, At, B0); PG8_MMA(1, 1, At, B1); PG8_BAR; PG8_SCHED;
.LBB0_1249:
	ds_read_b128 v[146:149], v141
	ds_read_b128 v[150:153], v141 offset:1024
	ds_read_b128 v[154:157], v141 offset:2048
	ds_read_b128 v[158:161], v141 offset:3072
	ds_read_b128 v[162:165], v142
	ds_read_b128 v[166:169], v142 offset:1024
	ds_read_b128 v[170:173], v142 offset:2048
	ds_read_b128 v[174:177], v142 offset:3072
	s_add_u32 s46, s14, s50
	s_addc_u32 s47, s15, s51
	s_add_u32 s53, s14, s44
	s_addc_u32 s54, s15, s45
	s_cmpk_eq_i32 s52, 0xa8
	s_cselect_b32 s49, s3, s47
	s_cselect_b32 s48, s2, s46
	s_cselect_b32 s47, s11, s54
	s_cselect_b32 s46, s10, s53
	s_mov_b32 m0, s57
	v_lshl_add_u64 v[212:213], s[14:15], 0, v[136:137]
	ds_read_b128 v[178:181], v143
	ds_read_b128 v[182:185], v143 offset:1024
	ds_read_b128 v[186:189], v143 offset:2048
	ds_read_b128 v[190:193], v143 offset:3072
	ds_read_b128 v[194:197], v143 offset:4096
	ds_read_b128 v[198:201], v143 offset:5120
	ds_read_b128 v[202:205], v143 offset:6144
	ds_read_b128 v[208:211], v143 offset:7168
	global_load_lds_dwordx4 v[212:213], off
	v_lshl_add_u64 v[212:213], s[14:15], 0, v[138:139]
	s_mov_b32 m0, s58
	s_nop 0
	global_load_lds_dwordx4 v[212:213], off
	s_waitcnt vmcnt(8)
	s_waitcnt lgkmcnt(0)
	s_barrier
	s_waitcnt lgkmcnt(0)
	v_mfma_f32_16x16x32_bf16 v[124:127], v[146:149], v[178:181], v[124:127]
	v_mfma_f32_16x16x32_bf16 v[120:123], v[154:157], v[178:181], v[120:123]
	v_mfma_f32_16x16x32_bf16 v[108:111], v[146:149], v[186:189], v[108:111]
	v_mfma_f32_16x16x32_bf16 v[104:107], v[154:157], v[186:189], v[104:107]
	v_mfma_f32_16x16x32_bf16 v[92:95], v[146:149], v[194:197], v[92:95]
	v_mfma_f32_16x16x32_bf16 v[88:91], v[154:157], v[194:197], v[88:91]
	v_mfma_f32_16x16x32_bf16 v[76:79], v[146:149], v[202:205], v[76:79]
	v_mfma_f32_16x16x32_bf16 v[72:75], v[154:157], v[202:205], v[72:75]
	v_mfma_f32_16x16x32_bf16 v[124:127], v[150:153], v[182:185], v[124:127]
	v_mfma_f32_16x16x32_bf16 v[120:123], v[158:161], v[182:185], v[120:123]
	v_mfma_f32_16x16x32_bf16 v[108:111], v[150:153], v[190:193], v[108:111]
	v_mfma_f32_16x16x32_bf16 v[104:107], v[158:161], v[190:193], v[104:107]
	v_mfma_f32_16x16x32_bf16 v[92:95], v[150:153], v[198:201], v[92:95]
	v_mfma_f32_16x16x32_bf16 v[88:91], v[158:161], v[198:201], v[88:91]
	v_mfma_f32_16x16x32_bf16 v[76:79], v[150:153], v[208:211], v[76:79]
	v_mfma_f32_16x16x32_bf16 v[72:75], v[158:161], v[208:211], v[72:75]
	v_mfma_f32_16x16x32_bf16 v[116:119], v[162:165], v[178:181], v[116:119]
	v_mfma_f32_16x16x32_bf16 v[112:115], v[170:173], v[178:181], v[112:115]
	v_mfma_f32_16x16x32_bf16 v[100:103], v[162:165], v[186:189], v[100:103]
	v_mfma_f32_16x16x32_bf16 v[96:99], v[170:173], v[186:189], v[96:99]
	v_mfma_f32_16x16x32_bf16 v[84:87], v[162:165], v[194:197], v[84:87]
	v_mfma_f32_16x16x32_bf16 v[80:83], v[170:173], v[194:197], v[80:83]
	v_mfma_f32_16x16x32_bf16 v[68:71], v[162:165], v[202:205], v[68:71]
	v_mfma_f32_16x16x32_bf16 v[64:67], v[170:173], v[202:205], v[64:67]
	v_mfma_f32_16x16x32_bf16 v[116:119], v[166:169], v[182:185], v[116:119]
	v_mfma_f32_16x16x32_bf16 v[112:115], v[174:177], v[182:185], v[112:115]
	v_mfma_f32_16x16x32_bf16 v[100:103], v[166:169], v[190:193], v[100:103]
	v_mfma_f32_16x16x32_bf16 v[96:99], v[174:177], v[190:193], v[96:99]
	v_mfma_f32_16x16x32_bf16 v[84:87], v[166:169], v[198:201], v[84:87]
	v_mfma_f32_16x16x32_bf16 v[80:83], v[174:177], v[198:201], v[80:83]
	v_mfma_f32_16x16x32_bf16 v[68:71], v[166:169], v[208:211], v[68:71]
	v_mfma_f32_16x16x32_bf16 v[64:67], v[174:177], v[208:211], v[64:67]
	s_barrier
	s_mov_b32 m0, s59
	v_lshl_add_u64 v[212:213], s[46:47], 0, v[130:131]
	s_add_u32 s54, s46, 0x2b4000
	ds_read_b128 v[178:181], v143 offset:16384
	ds_read_b128 v[182:185], v143 offset:17408
	ds_read_b128 v[186:189], v143 offset:18432
	ds_read_b128 v[190:193], v143 offset:19456
	ds_read_b128 v[194:197], v143 offset:20480
	ds_read_b128 v[198:201], v143 offset:21504
	ds_read_b128 v[202:205], v143 offset:22528
	ds_read_b128 v[208:211], v143 offset:23552
	global_load_lds_dwordx4 v[212:213], off
	v_lshl_add_u64 v[214:215], s[46:47], 0, v[134:135]
	s_mov_b32 m0, s60
	s_addc_u32 s55, s47, 0
	global_load_lds_dwordx4 v[214:215], off
	v_lshl_add_u64 v[216:217], s[54:55], 0, v[130:131]
	s_mov_b32 m0, s61
	v_lshl_add_u64 v[218:219], s[48:49], 0, v[132:133]
	global_load_lds_dwordx4 v[216:217], off
	v_lshl_add_u64 v[216:217], s[54:55], 0, v[134:135]
	s_mov_b32 m0, s62
	s_nop 0
	global_load_lds_dwordx4 v[216:217], off
	v_lshl_add_u64 v[216:217], s[48:49], 0, v[128:129]
	s_mov_b32 m0, s17
	s_nop 0
	global_load_lds_dwordx4 v[216:217], off
	s_mov_b32 m0, s19
	s_nop 0
	global_load_lds_dwordx4 v[218:219], off
	s_nop 0
	s_waitcnt vmcnt(8)
	s_waitcnt lgkmcnt(0)
	s_barrier
; #define PG8_STAGE(bufoff, gbase, voff) do { _Pragma("unroll") for (int _i = 0; _i < 2; ++_i) \
;         __builtin_amdgcn_global_load_lds((const unsigned*)((const char*)(gbase) + (voff)[_i]), (PG8_LAS unsigned*)(lds + (bufoff) + ldsw + _i * 8192), 16, 0, 0); } while (0)
; #define PG8_STAGE_NT(bufoff, gbase, voff) do { _Pragma("unroll") for (int _i = 0; _i < 2; ++_i) \
;         __builtin_amdgcn_global_load_lds((const unsigned*)((const char*)(gbase) + (voff)[_i]), (PG8_LAS unsigned*)(lds + (bufoff) + ldsw + _i * 8192), 16, 0, PG8_B_AUX); } while (0)
; #define PG8_LDA(dst, b, h) do { _Pragma("unroll") for (int m = 0; m < 4; ++m) _Pragma("unroll") for (int k = 0; k < 2; ++k) dst[m][k] = *(const PG8_LAS bf16x8*)(lds + PG8_SA(b, h) + aoff + m * 2048 + k * 1024); } while (0)
; #define PG8_LDB(dst, b, h) do { _Pragma("unroll") for (int n = 0; n < 2; ++n) _Pragma("unroll") for (int k = 0; k < 2; ++k) dst[n][k] = *(const PG8_LAS bf16x8*)(lds + PG8_SB(b, h) + boff + n * 2048 + k * 1024); } while (0)
; #define PG8_MMA(ai, bj, At, Bt) do { __builtin_amdgcn_s_setprio(1); _Pragma("unroll") for (int m = 0; m < 4; ++m) _Pragma("unroll") for (int n = 0; n < 2; ++n) _Pragma("unroll") for (int k = 0; k < 2; ++k) \
;         acc[ai][bj][m][n] = __builtin_amdgcn_mfma_f32_16x16x32_bf16(Bt[n][k], At[m][k], acc[ai][bj][m][n], 0, 0, 0); __builtin_amdgcn_s_setprio(0); } while (0)
; #define PG8_WAIT_V(n) asm volatile("s_waitcnt vmcnt(" #n ")" ::: "memory")
; #define PG8_WAIT_L(n) asm volatile("s_waitcnt lgkmcnt(" #n ")" ::: "memory")
; template <class Epi, class Sched, bool ALIGN_EPI = false, bool SP2 = false>
; __device__ __forceinline__ void gemm_phase(PG8_LAS unsigned char* lds, const Gemm g, const Sched& S, const Epi& E, int wid) {
;     ...
;             PG8_WAIT_V(8); PG8_WAIT_L(0); PG8_BAR; PG8_MMA(0, 0, At, B0); PG8_MMA(0, 1, At, B1); PG8_BAR; PG8_SCHED;
;             PG8_LDA(At, 0, 1); PG8_STAGE_NT(PG8_SB(0, 0), b2, voffB); PG8_STAGE_NT(PG8_SB(0, 1), b2 + hstepB, voffB); PG8_STAGE(PG8_SA(0, 0), a2, voffA);
;             PG8_WAIT_V(8); PG8_WAIT_L(0); PG8_BAR; PG8_MMA(1, 0, At, B0); PG8_MMA(1, 1, At, B1); PG8_BAR; PG8_SCHED;
;             PG8_LDB(B0, 1, 0); PG8_LDB(B1, 1, 1); PG8_SCHED; PG8_LDA(At, 1, 0); PG8_STAGE(PG8_SA(0, 1), a2 + hstepA, voffA);
;             PG8_WAIT_V(8); PG8_WAIT_L(0); PG8_BAR; PG8_MMA(0, 0, At, B0); PG8_MMA(0, 1, At, B1); PG8_BAR; PG8_SCHED;
	s_waitcnt lgkmcnt(0)
	v_mfma_f32_16x16x32_bf16 v[60:63], v[146:149], v[178:181], v[60:63]
	v_mfma_f32_16x16x32_bf16 v[56:59], v[154:157], v[178:181], v[56:59]
	v_mfma_f32_16x16x32_bf16 v[44:47], v[146:149], v[186:189], v[44:47]
	v_mfma_f32_16x16x32_bf16 v[40:43], v[154:157], v[186:189], v[40:43]
	v_mfma_f32_16x16x32_bf16 v[28:31], v[146:149], v[194:197], v[28:31]
	v_mfma_f32_16x16x32_bf16 v[24:27], v[154:157], v[194:197], v[24:27]
	v_mfma_f32_16x16x32_bf16 v[12:15], v[146:149], v[202:205], v[12:15]
	v_mfma_f32_16x16x32_bf16 v[8:11], v[154:157], v[202:205], v[8:11]
	v_mfma_f32_16x16x32_bf16 v[60:63], v[150:153], v[182:185], v[60:63]
	v_mfma_f32_16x16x32_bf16 v[56:59], v[158:161], v[182:185], v[56:59]
	v_mfma_f32_16x16x32_bf16 v[44:47], v[150:153], v[190:193], v[44:47]
	v_mfma_f32_16x16x32_bf16 v[40:43], v[158:161], v[190:193], v[40:43]
	v_mfma_f32_16x16x32_bf16 v[28:31], v[150:153], v[198:201], v[28:31]
	v_mfma_f32_16x16x32_bf16 v[24:27], v[158:161], v[198:201], v[24:27]
	v_mfma_f32_16x16x32_bf16 v[12:15], v[150:153], v[208:211], v[12:15]
	v_mfma_f32_16x16x32_bf16 v[8:11], v[158:161], v[208:211], v[8:11]
	v_mfma_f32_16x16x32_bf16 v[52:55], v[162:165], v[178:181], v[52:55]
	v_mfma_f32_16x16x32_bf16 v[48:51], v[170:173], v[178:181], v[48:51]
	v_mfma_f32_16x16x32_bf16 v[36:39], v[162:165], v[186:189], v[36:39]
	v_mfma_f32_16x16x32_bf16 v[32:35], v[170:173], v[186:189], v[32:35]
	v_mfma_f32_16x16x32_bf16 v[20:23], v[162:165], v[194:197], v[20:23]
	v_mfma_f32_16x16x32_bf16 v[16:19], v[170:173], v[194:197], v[16:19]
	v_mfma_f32_16x16x32_bf16 v[4:7], v[162:165], v[202:205], v[4:7]
	v_mfma_f32_16x16x32_bf16 v[0:3], v[170:173], v[202:205], v[0:3]
	v_mfma_f32_16x16x32_bf16 v[52:55], v[166:169], v[182:185], v[52:55]
	v_mfma_f32_16x16x32_bf16 v[48:51], v[174:177], v[182:185], v[48:51]
	v_mfma_f32_16x16x32_bf16 v[36:39], v[166:169], v[190:193], v[36:39]
	v_mfma_f32_16x16x32_bf16 v[32:35], v[174:177], v[190:193], v[32:35]
	v_mfma_f32_16x16x32_bf16 v[20:23], v[166:169], v[198:201], v[20:23]
	v_mfma_f32_16x16x32_bf16 v[16:19], v[174:177], v[198:201], v[16:19]
	v_mfma_f32_16x16x32_bf16 v[4:7], v[166:169], v[208:211], v[4:7]
	v_mfma_f32_16x16x32_bf16 v[0:3], v[174:177], v[208:211], v[0:3]
	s_barrier
	ds_read_b128 v[146:149], v144
	ds_read_b128 v[150:153], v144 offset:1024
	ds_read_b128 v[154:157], v144 offset:2048
	ds_read_b128 v[158:161], v144 offset:3072
	ds_read_b128 v[162:165], v145
	ds_read_b128 v[166:169], v145 offset:1024
	ds_read_b128 v[170:173], v145 offset:2048
	ds_read_b128 v[174:177], v145 offset:3072
	s_add_u32 s48, s48, 0x2b4000
	s_addc_u32 s49, s49, 0
	s_mov_b32 m0, s22
	v_lshl_add_u64 v[220:221], s[48:49], 0, v[128:129]
	ds_read_b128 v[178:181], v143 offset:32768
	ds_read_b128 v[182:185], v143 offset:33792
	ds_read_b128 v[186:189], v143 offset:34816
	ds_read_b128 v[190:193], v143 offset:35840
	ds_read_b128 v[194:197], v143 offset:36864
	ds_read_b128 v[198:201], v143 offset:37888
	ds_read_b128 v[202:205], v143 offset:38912
	ds_read_b128 v[208:211], v143 offset:39936
	global_load_lds_dwordx4 v[220:221], off
	v_lshl_add_u64 v[220:221], s[48:49], 0, v[132:133]
	s_mov_b32 m0, s23
	s_nop 0
	global_load_lds_dwordx4 v[220:221], off
	s_nop 0
	s_waitcnt vmcnt(8)
	s_waitcnt lgkmcnt(0)
	s_barrier
	s_waitcnt lgkmcnt(0)
	v_mfma_f32_16x16x32_bf16 v[124:127], v[146:149], v[178:181], v[124:127]
	v_mfma_f32_16x16x32_bf16 v[120:123], v[154:157], v[178:181], v[120:123]
	v_mfma_f32_16x16x32_bf16 v[108:111], v[146:149], v[186:189], v[108:111]
	v_mfma_f32_16x16x32_bf16 v[104:107], v[154:157], v[186:189], v[104:107]
	v_mfma_f32_16x16x32_bf16 v[92:95], v[146:149], v[194:197], v[92:95]
	v_mfma_f32_16x16x32_bf16 v[88:91], v[154:157], v[194:197], v[88:91]
	v_mfma_f32_16x16x32_bf16 v[76:79], v[146:149], v[202:205], v[76:79]
	v_mfma_f32_16x16x32_bf16 v[72:75], v[154:157], v[202:205], v[72:75]
	v_mfma_f32_16x16x32_bf16 v[124:127], v[150:153], v[182:185], v[124:127]
	v_mfma_f32_16x16x32_bf16 v[120:123], v[158:161], v[182:185], v[120:123]
	v_mfma_f32_16x16x32_bf16 v[108:111], v[150:153], v[190:193], v[108:111]
	v_mfma_f32_16x16x32_bf16 v[104:107], v[158:161], v[190:193], v[104:107]
	v_mfma_f32_16x16x32_bf16 v[92:95], v[150:153], v[198:201], v[92:95]
	v_mfma_f32_16x16x32_bf16 v[88:91], v[158:161], v[198:201], v[88:91]
	v_mfma_f32_16x16x32_bf16 v[76:79], v[150:153], v[208:211], v[76:79]
	v_mfma_f32_16x16x32_bf16 v[72:75], v[158:161], v[208:211], v[72:75]
	v_mfma_f32_16x16x32_bf16 v[116:119], v[162:165], v[178:181], v[116:119]
	v_mfma_f32_16x16x32_bf16 v[112:115], v[170:173], v[178:181], v[112:115]
	v_mfma_f32_16x16x32_bf16 v[100:103], v[162:165], v[186:189], v[100:103]
	v_mfma_f32_16x16x32_bf16 v[96:99], v[170:173], v[186:189], v[96:99]
	v_mfma_f32_16x16x32_bf16 v[84:87], v[162:165], v[194:197], v[84:87]
	v_mfma_f32_16x16x32_bf16 v[80:83], v[170:173], v[194:197], v[80:83]
	v_mfma_f32_16x16x32_bf16 v[68:71], v[162:165], v[202:205], v[68:71]
	v_mfma_f32_16x16x32_bf16 v[64:67], v[170:173], v[202:205], v[64:67]
	v_mfma_f32_16x16x32_bf16 v[116:119], v[166:169], v[182:185], v[116:119]
	v_mfma_f32_16x16x32_bf16 v[112:115], v[174:177], v[182:185], v[112:115]
	v_mfma_f32_16x16x32_bf16 v[100:103], v[166:169], v[190:193], v[100:103]
	v_mfma_f32_16x16x32_bf16 v[96:99], v[174:177], v[190:193], v[96:99]
	v_mfma_f32_16x16x32_bf16 v[84:87], v[166:169], v[198:201], v[84:87]
	v_mfma_f32_16x16x32_bf16 v[80:83], v[174:177], v[198:201], v[80:83]
	v_mfma_f32_16x16x32_bf16 v[68:71], v[166:169], v[208:211], v[68:71]
	v_mfma_f32_16x16x32_bf16 v[64:67], v[174:177], v[208:211], v[64:67]
	s_barrier
; #define PG8_STAGE(bufoff, gbase, voff) do { _Pragma("unroll") for (int _i = 0; _i < 2; ++_i) \
;         __builtin_amdgcn_global_load_lds((const unsigned*)((const char*)(gbase) + (voff)[_i]), (PG8_LAS unsigned*)(lds + (bufoff) + ldsw + _i * 8192), 16, 0, 0); } while (0)
; #define PG8_STAGE_NT(bufoff, gbase, voff) do { _Pragma("unroll") for (int _i = 0; _i < 2; ++_i) \
;         __builtin_amdgcn_global_load_lds((const unsigned*)((const char*)(gbase) + (voff)[_i]), (PG8_LAS unsigned*)(lds + (bufoff) + ldsw + _i * 8192), 16, 0, PG8_B_AUX); } while (0)
; #define PG8_LDA(dst, b, h) do { _Pragma("unroll") for (int m = 0; m < 4; ++m) _Pragma("unroll") for (int k = 0; k < 2; ++k) dst[m][k] = *(const PG8_LAS bf16x8*)(lds + PG8_SA(b, h) + aoff + m * 2048 + k * 1024); } while (0)
; #define PG8_MMA(ai, bj, At, Bt) do { __builtin_amdgcn_s_setprio(1); _Pragma("unroll") for (int m = 0; m < 4; ++m) _Pragma("unroll") for (int n = 0; n < 2; ++n) _Pragma("unroll") for (int k = 0; k < 2; ++k) \
;         acc[ai][bj][m][n] = __builtin_amdgcn_mfma_f32_16x16x32_bf16(Bt[n][k], At[m][k], acc[ai][bj][m][n], 0, 0, 0); __builtin_amdgcn_s_setprio(0); } while (0)
; #define PG8_WAIT_V(n) asm volatile("s_waitcnt vmcnt(" #n ")" ::: "memory")
; #define PG8_WAIT_L(n) asm volatile("s_waitcnt lgkmcnt(" #n ")" ::: "memory")
; #define PG8_BAR __builtin_amdgcn_s_barrier()
; #define PG8_SCHED __builtin_amdgcn_sched_barrier(0)
; template <class Epi, class Sched, bool ALIGN_EPI = false, bool SP2 = false>
; __device__ __forceinline__ void gemm_phase(PG8_LAS unsigned char* lds, const Gemm g, const Sched& S, const Epi& E, int wid) {
;     ...
;             PG8_LDA(At, 1, 1); PG8_STAGE_NT(PG8_SB(1, 0), b3, voffB); PG8_STAGE_NT(PG8_SB(1, 1), b3 + hstepB, voffB); PG8_STAGE(PG8_SA(1, 0), a3, voffA);
;             PG8_WAIT_V(8); PG8_WAIT_L(0); PG8_BAR; PG8_MMA(1, 0, At, B0); PG8_MMA(1, 1, At, B1); PG8_BAR; PG8_SCHED;
;     ...
;     PG8_WAIT_V(0);
;     if constexpr (!ALIGN_EPI) { if (wr == 0) PG8_BAR; }
;     PG8_BAR;
	s_mov_b32 m0, s63
	v_lshl_add_u64 v[212:213], v[212:213], 0, s[4:5]
	s_add_u32 s46, s46, 0x2b4080
	ds_read_b128 v[178:181], v143 offset:49152
	ds_read_b128 v[182:185], v143 offset:50176
	ds_read_b128 v[186:189], v143 offset:51200
	ds_read_b128 v[190:193], v143 offset:52224
	ds_read_b128 v[194:197], v143 offset:53248
	ds_read_b128 v[198:201], v143 offset:54272
	ds_read_b128 v[202:205], v143 offset:55296
	ds_read_b128 v[208:211], v143 offset:56320
	global_load_lds_dwordx4 v[212:213], off
	v_lshl_add_u64 v[212:213], v[214:215], 0, s[4:5]
	s_mov_b32 m0, s64
	s_addc_u32 s47, s47, 0
	global_load_lds_dwordx4 v[212:213], off
	v_lshl_add_u64 v[212:213], s[46:47], 0, v[130:131]
	s_mov_b32 m0, s65
	s_nop 0
	global_load_lds_dwordx4 v[212:213], off
	v_lshl_add_u64 v[212:213], s[46:47], 0, v[134:135]
	s_mov_b32 m0, s66
	s_nop 0
	global_load_lds_dwordx4 v[212:213], off
	v_lshl_add_u64 v[212:213], v[216:217], 0, s[4:5]
	s_mov_b32 m0, s25
	s_nop 0
	global_load_lds_dwordx4 v[212:213], off
	v_lshl_add_u64 v[212:213], v[218:219], 0, s[4:5]
	s_mov_b32 m0, s56
	s_nop 0
	global_load_lds_dwordx4 v[212:213], off
	s_waitcnt vmcnt(8)
	s_waitcnt lgkmcnt(0)
	s_barrier
	s_waitcnt lgkmcnt(0)
	v_mfma_f32_16x16x32_bf16 v[60:63], v[146:149], v[178:181], v[60:63]
	v_mfma_f32_16x16x32_bf16 v[56:59], v[154:157], v[178:181], v[56:59]
	v_mfma_f32_16x16x32_bf16 v[44:47], v[146:149], v[186:189], v[44:47]
	v_mfma_f32_16x16x32_bf16 v[40:43], v[154:157], v[186:189], v[40:43]
	v_mfma_f32_16x16x32_bf16 v[28:31], v[146:149], v[194:197], v[28:31]
	v_mfma_f32_16x16x32_bf16 v[24:27], v[154:157], v[194:197], v[24:27]
	v_mfma_f32_16x16x32_bf16 v[12:15], v[146:149], v[202:205], v[12:15]
	v_mfma_f32_16x16x32_bf16 v[8:11], v[154:157], v[202:205], v[8:11]
	v_mfma_f32_16x16x32_bf16 v[60:63], v[150:153], v[182:185], v[60:63]
	v_mfma_f32_16x16x32_bf16 v[56:59], v[158:161], v[182:185], v[56:59]
	v_mfma_f32_16x16x32_bf16 v[44:47], v[150:153], v[190:193], v[44:47]
	v_mfma_f32_16x16x32_bf16 v[40:43], v[158:161], v[190:193], v[40:43]
	v_mfma_f32_16x16x32_bf16 v[28:31], v[150:153], v[198:201], v[28:31]
	v_mfma_f32_16x16x32_bf16 v[24:27], v[158:161], v[198:201], v[24:27]
	v_mfma_f32_16x16x32_bf16 v[12:15], v[150:153], v[208:211], v[12:15]
	v_mfma_f32_16x16x32_bf16 v[8:11], v[158:161], v[208:211], v[8:11]
	v_mfma_f32_16x16x32_bf16 v[52:55], v[162:165], v[178:181], v[52:55]
	v_mfma_f32_16x16x32_bf16 v[48:51], v[170:173], v[178:181], v[48:51]
	v_mfma_f32_16x16x32_bf16 v[36:39], v[162:165], v[186:189], v[36:39]
	v_mfma_f32_16x16x32_bf16 v[32:35], v[170:173], v[186:189], v[32:35]
	v_mfma_f32_16x16x32_bf16 v[20:23], v[162:165], v[194:197], v[20:23]
	v_mfma_f32_16x16x32_bf16 v[16:19], v[170:173], v[194:197], v[16:19]
	v_mfma_f32_16x16x32_bf16 v[4:7], v[162:165], v[202:205], v[4:7]
	v_mfma_f32_16x16x32_bf16 v[0:3], v[170:173], v[202:205], v[0:3]
	v_mfma_f32_16x16x32_bf16 v[52:55], v[166:169], v[182:185], v[52:55]
	v_mfma_f32_16x16x32_bf16 v[48:51], v[174:177], v[182:185], v[48:51]
	v_mfma_f32_16x16x32_bf16 v[36:39], v[166:169], v[190:193], v[36:39]
	v_mfma_f32_16x16x32_bf16 v[32:35], v[174:177], v[190:193], v[32:35]
	v_mfma_f32_16x16x32_bf16 v[20:23], v[166:169], v[198:201], v[20:23]
	v_mfma_f32_16x16x32_bf16 v[16:19], v[174:177], v[198:201], v[16:19]
	v_mfma_f32_16x16x32_bf16 v[4:7], v[166:169], v[208:211], v[4:7]
	v_mfma_f32_16x16x32_bf16 v[0:3], v[174:177], v[208:211], v[0:3]
	s_barrier
	s_add_i32 s52, s52, 2
	s_add_u32 s50, s50, 0x100
	s_addc_u32 s51, s51, 0
	s_add_u32 s44, s44, 0x100
	s_addc_u32 s45, s45, 0
	v_lshl_add_u64 v[136:137], v[136:137], 0, s[42:43]
	s_cmpk_lt_u32 s52, 0xaa
	v_lshl_add_u64 v[138:139], v[138:139], 0, s[42:43]
	s_cbranch_scc1 .LBB0_1249
	s_waitcnt vmcnt(0)
	s_cmpk_lt_u32 s95, 0x100
	s_cselect_b64 s[44:45], -1, 0
	s_cmpk_gt_u32 s95, 0xff
	s_cbranch_scc1 .LBB0_1252
	s_barrier

; #define PG8_STAGE(bufoff, gbase, voff) do { _Pragma("unroll") for (int _i = 0; _i < 2; ++_i) \
;         __builtin_amdgcn_global_load_lds((const unsigned*)((const char*)(gbase) + (voff)[_i]), (PG8_LAS unsigned*)(lds + (bufoff) + ldsw + _i * 8192), 16, 0, 0); } while (0)
; #define PG8_STAGE_NT(bufoff, gbase, voff) do { _Pragma("unroll") for (int _i = 0; _i < 2; ++_i) \
;         __builtin_amdgcn_global_load_lds((const unsigned*)((const char*)(gbase) + (voff)[_i]), (PG8_LAS unsigned*)(lds + (bufoff) + ldsw + _i * 8192), 16, 0, PG8_B_AUX); } while (0)
; #define PG8_LDA(dst, b, h) do { _Pragma("unroll") for (int m = 0; m < 4; ++m) _Pragma("unroll") for (int k = 0; k < 2; ++k) dst[m][k] = *(const PG8_LAS bf16x8*)(lds + PG8_SA(b, h) + aoff + m * 2048 + k * 1024); } while (0)
; #define PG8_LDB(dst, b, h) do { _Pragma("unroll") for (int n = 0; n < 2; ++n) _Pragma("unroll") for (int k = 0; k < 2; ++k) dst[n][k] = *(const PG8_LAS bf16x8*)(lds + PG8_SB(b, h) + boff + n * 2048 + k * 1024); } while (0)
; #define PG8_WAIT_V(n) asm volatile("s_waitcnt vmcnt(" #n ")" ::: "memory")
; #define PG8_WAIT_L(n) asm volatile("s_waitcnt lgkmcnt(" #n ")" ::: "memory")
; #define PG8_BAR __builtin_amdgcn_s_barrier()
; #define PG8_SCHED __builtin_amdgcn_sched_barrier(0)
; template <class Epi, class Sched, bool ALIGN_EPI = false, bool SP2 = false>
; __device__ __forceinline__ void gemm_phase(PG8_LAS unsigned char* lds, const Gemm g, const Sched& S, const Epi& E, int wid) {
;     ...
;             const bool last = (t == nt - 2);
;             const char* a1 = cA + (size_t)(t + 1) * kstep;
;             const char* a2 = last ? nA : cA + (size_t)(t + 2) * kstep; const char* b2 = last ? nB : cB + (size_t)(t + 2) * kstep;
;             const char* a3 = a2 + kstep; const char* b3 = b2 + kstep;
;             if (last && has_next) S.a_ready(nxt);
;             if constexpr (SP2) {
;             PG8_LDB(B0, 0, 0); PG8_LDB(B1, 0, 1); PG8_SCHED; PG8_LDA(At, 0, 0); PG8_STAGE(PG8_SA(1, 1), a1 + hstepA, voffA);
;             PG8_WAIT_V(8); PG8_WAIT_L(0); PG8_BAR; PG8_MMA(0, 0, At, B0); PG8_MMA(0, 1, At, B1); PG8_BAR; PG8_SCHED;
;             PG8_LDA(At, 0, 1); PG8_STAGE_NT(PG8_SB(0, 0), b2, voffB); PG8_STAGE_NT(PG8_SB(0, 1), b2 + hstepB, voffB); PG8_STAGE(PG8_SA(0, 0), a2, voffA);
;             PG8_WAIT_V(8); PG8_WAIT_L(0); PG8_BAR; PG8_MMA(1, 0, At, B0); PG8_MMA(1, 1, At, B1); PG8_BAR; PG8_SCHED;
.LBB0_1307:
	ds_read_b128 v[146:149], v141
	ds_read_b128 v[150:153], v141 offset:1024
	ds_read_b128 v[154:157], v141 offset:2048
	ds_read_b128 v[158:161], v141 offset:3072
	ds_read_b128 v[162:165], v142
	ds_read_b128 v[166:169], v142 offset:1024
	ds_read_b128 v[170:173], v142 offset:2048
	ds_read_b128 v[174:177], v142 offset:3072
	s_add_u32 s30, s14, s21
	s_addc_u32 s31, s15, s40
	s_add_u32 s48, s14, s8
	s_addc_u32 s49, s15, s9
	s_cmpk_eq_i32 s41, 0xa8
	s_cselect_b32 s39, s3, s31
	s_cselect_b32 s38, s2, s30
	s_cselect_b32 s31, s11, s49
	s_cselect_b32 s30, s10, s48
	s_mov_b32 m0, s57
	v_lshl_add_u64 v[202:203], s[14:15], 0, v[136:137]
	ds_read_b128 v[178:181], v143
	ds_read_b128 v[182:185], v143 offset:1024
	ds_read_b128 v[186:189], v143 offset:2048
	ds_read_b128 v[190:193], v143 offset:3072
	ds_read_b128 v[194:197], v143 offset:4096
	ds_read_b128 v[198:201], v143 offset:5120
	ds_read_b128 v[208:211], v143 offset:6144
	ds_read_b128 v[212:215], v143 offset:7168
	global_load_lds_dwordx4 v[202:203], off
	v_lshl_add_u64 v[202:203], s[14:15], 0, v[138:139]
	s_mov_b32 m0, s58
	s_nop 0
	global_load_lds_dwordx4 v[202:203], off
	s_waitcnt vmcnt(8)
	s_waitcnt lgkmcnt(0)
	s_barrier
	s_waitcnt lgkmcnt(0)
	v_mfma_f32_16x16x32_bf16 v[124:127], v[146:149], v[178:181], v[124:127]
	v_mfma_f32_16x16x32_bf16 v[120:123], v[154:157], v[178:181], v[120:123]
	v_mfma_f32_16x16x32_bf16 v[108:111], v[146:149], v[186:189], v[108:111]
	v_mfma_f32_16x16x32_bf16 v[104:107], v[154:157], v[186:189], v[104:107]
	v_mfma_f32_16x16x32_bf16 v[92:95], v[146:149], v[194:197], v[92:95]
	v_mfma_f32_16x16x32_bf16 v[88:91], v[154:157], v[194:197], v[88:91]
	v_mfma_f32_16x16x32_bf16 v[76:79], v[146:149], v[208:211], v[76:79]
	v_mfma_f32_16x16x32_bf16 v[72:75], v[154:157], v[208:211], v[72:75]
	v_mfma_f32_16x16x32_bf16 v[124:127], v[150:153], v[182:185], v[124:127]
	v_mfma_f32_16x16x32_bf16 v[120:123], v[158:161], v[182:185], v[120:123]
	v_mfma_f32_16x16x32_bf16 v[108:111], v[150:153], v[190:193], v[108:111]
	v_mfma_f32_16x16x32_bf16 v[104:107], v[158:161], v[190:193], v[104:107]
	v_mfma_f32_16x16x32_bf16 v[92:95], v[150:153], v[198:201], v[92:95]
	v_mfma_f32_16x16x32_bf16 v[88:91], v[158:161], v[198:201], v[88:91]
	v_mfma_f32_16x16x32_bf16 v[76:79], v[150:153], v[212:215], v[76:79]
	v_mfma_f32_16x16x32_bf16 v[72:75], v[158:161], v[212:215], v[72:75]
	v_mfma_f32_16x16x32_bf16 v[116:119], v[162:165], v[178:181], v[116:119]
	v_mfma_f32_16x16x32_bf16 v[112:115], v[170:173], v[178:181], v[112:115]
	v_mfma_f32_16x16x32_bf16 v[100:103], v[162:165], v[186:189], v[100:103]
	v_mfma_f32_16x16x32_bf16 v[96:99], v[170:173], v[186:189], v[96:99]
	v_mfma_f32_16x16x32_bf16 v[84:87], v[162:165], v[194:197], v[84:87]
	v_mfma_f32_16x16x32_bf16 v[80:83], v[170:173], v[194:197], v[80:83]
	v_mfma_f32_16x16x32_bf16 v[68:71], v[162:165], v[208:211], v[68:71]
	v_mfma_f32_16x16x32_bf16 v[64:67], v[170:173], v[208:211], v[64:67]
	v_mfma_f32_16x16x32_bf16 v[116:119], v[166:169], v[182:185], v[116:119]
	v_mfma_f32_16x16x32_bf16 v[112:115], v[174:177], v[182:185], v[112:115]
	v_mfma_f32_16x16x32_bf16 v[100:103], v[166:169], v[190:193], v[100:103]
	v_mfma_f32_16x16x32_bf16 v[96:99], v[174:177], v[190:193], v[96:99]
	v_mfma_f32_16x16x32_bf16 v[84:87], v[166:169], v[198:201], v[84:87]
	v_mfma_f32_16x16x32_bf16 v[80:83], v[174:177], v[198:201], v[80:83]
	v_mfma_f32_16x16x32_bf16 v[68:71], v[166:169], v[212:215], v[68:71]
	v_mfma_f32_16x16x32_bf16 v[64:67], v[174:177], v[212:215], v[64:67]
	s_barrier
	s_mov_b32 m0, s59
	v_lshl_add_u64 v[202:203], s[30:31], 0, v[130:131]
	s_add_u32 s48, s30, 0x2b4000
	ds_read_b128 v[178:181], v143 offset:16384
	ds_read_b128 v[182:185], v143 offset:17408
	ds_read_b128 v[186:189], v143 offset:18432
	ds_read_b128 v[190:193], v143 offset:19456
	ds_read_b128 v[194:197], v143 offset:20480
	ds_read_b128 v[198:201], v143 offset:21504
	ds_read_b128 v[208:211], v143 offset:22528
	ds_read_b128 v[212:215], v143 offset:23552
	global_load_lds_dwordx4 v[202:203], off
	v_lshl_add_u64 v[216:217], s[30:31], 0, v[134:135]
	s_mov_b32 m0, s60
	s_addc_u32 s49, s31, 0
	global_load_lds_dwordx4 v[216:217], off
	v_lshl_add_u64 v[218:219], s[48:49], 0, v[130:131]
	s_mov_b32 m0, s61
	v_lshl_add_u64 v[220:221], s[38:39], 0, v[132:133]
	global_load_lds_dwordx4 v[218:219], off
	v_lshl_add_u64 v[218:219], s[48:49], 0, v[134:135]
	s_mov_b32 m0, s62
	s_nop 0
	global_load_lds_dwordx4 v[218:219], off
	v_lshl_add_u64 v[218:219], s[38:39], 0, v[128:129]
	s_mov_b32 m0, s17
	s_nop 0
	global_load_lds_dwordx4 v[218:219], off
	s_mov_b32 m0, s19
	s_nop 0
	global_load_lds_dwordx4 v[220:221], off
	s_nop 0
	s_waitcnt vmcnt(8)
	s_waitcnt lgkmcnt(0)
	s_barrier
; #define PG8_STAGE(bufoff, gbase, voff) do { _Pragma("unroll") for (int _i = 0; _i < 2; ++_i) \
;         __builtin_amdgcn_global_load_lds((const unsigned*)((const char*)(gbase) + (voff)[_i]), (PG8_LAS unsigned*)(lds + (bufoff) + ldsw + _i * 8192), 16, 0, 0); } while (0)
; #define PG8_STAGE_NT(bufoff, gbase, voff) do { _Pragma("unroll") for (int _i = 0; _i < 2; ++_i) \
;         __builtin_amdgcn_global_load_lds((const unsigned*)((const char*)(gbase) + (voff)[_i]), (PG8_LAS unsigned*)(lds + (bufoff) + ldsw + _i * 8192), 16, 0, PG8_B_AUX); } while (0)
; #define PG8_LDA(dst, b, h) do { _Pragma("unroll") for (int m = 0; m < 4; ++m) _Pragma("unroll") for (int k = 0; k < 2; ++k) dst[m][k] = *(const PG8_LAS bf16x8*)(lds + PG8_SA(b, h) + aoff + m * 2048 + k * 1024); } while (0)
; #define PG8_LDB(dst, b, h) do { _Pragma("unroll") for (int n = 0; n < 2; ++n) _Pragma("unroll") for (int k = 0; k < 2; ++k) dst[n][k] = *(const PG8_LAS bf16x8*)(lds + PG8_SB(b, h) + boff + n * 2048 + k * 1024); } while (0)
; #define PG8_MMA(ai, bj, At, Bt) do { __builtin_amdgcn_s_setprio(1); _Pragma("unroll") for (int m = 0; m < 4; ++m) _Pragma("unroll") for (int n = 0; n < 2; ++n) _Pragma("unroll") for (int k = 0; k < 2; ++k) \
;         acc[ai][bj][m][n] = __builtin_amdgcn_mfma_f32_16x16x32_bf16(Bt[n][k], At[m][k], acc[ai][bj][m][n], 0, 0, 0); __builtin_amdgcn_s_setprio(0); } while (0)
; #define PG8_WAIT_V(n) asm volatile("s_waitcnt vmcnt(" #n ")" ::: "memory")
; #define PG8_WAIT_L(n) asm volatile("s_waitcnt lgkmcnt(" #n ")" ::: "memory")
; template <class Epi, class Sched, bool ALIGN_EPI = false, bool SP2 = false>
; __device__ __forceinline__ void gemm_phase(PG8_LAS unsigned char* lds, const Gemm g, const Sched& S, const Epi& E, int wid) {
;     ...
;             PG8_WAIT_V(8); PG8_WAIT_L(0); PG8_BAR; PG8_MMA(0, 0, At, B0); PG8_MMA(0, 1, At, B1); PG8_BAR; PG8_SCHED;
;             PG8_LDA(At, 0, 1); PG8_STAGE_NT(PG8_SB(0, 0), b2, voffB); PG8_STAGE_NT(PG8_SB(0, 1), b2 + hstepB, voffB); PG8_STAGE(PG8_SA(0, 0), a2, voffA);
;             PG8_WAIT_V(8); PG8_WAIT_L(0); PG8_BAR; PG8_MMA(1, 0, At, B0); PG8_MMA(1, 1, At, B1); PG8_BAR; PG8_SCHED;
;             PG8_LDB(B0, 1, 0); PG8_LDB(B1, 1, 1); PG8_SCHED; PG8_LDA(At, 1, 0); PG8_STAGE(PG8_SA(0, 1), a2 + hstepA, voffA);
;             PG8_WAIT_V(8); PG8_WAIT_L(0); PG8_BAR; PG8_MMA(0, 0, At, B0); PG8_MMA(0, 1, At, B1); PG8_BAR; PG8_SCHED;
	s_waitcnt lgkmcnt(0)
	v_mfma_f32_16x16x32_bf16 v[60:63], v[146:149], v[178:181], v[60:63]
	v_mfma_f32_16x16x32_bf16 v[56:59], v[154:157], v[178:181], v[56:59]
	v_mfma_f32_16x16x32_bf16 v[44:47], v[146:149], v[186:189], v[44:47]
	v_mfma_f32_16x16x32_bf16 v[40:43], v[154:157], v[186:189], v[40:43]
	v_mfma_f32_16x16x32_bf16 v[28:31], v[146:149], v[194:197], v[28:31]
	v_mfma_f32_16x16x32_bf16 v[24:27], v[154:157], v[194:197], v[24:27]
	v_mfma_f32_16x16x32_bf16 v[12:15], v[146:149], v[208:211], v[12:15]
	v_mfma_f32_16x16x32_bf16 v[8:11], v[154:157], v[208:211], v[8:11]
	v_mfma_f32_16x16x32_bf16 v[60:63], v[150:153], v[182:185], v[60:63]
	v_mfma_f32_16x16x32_bf16 v[56:59], v[158:161], v[182:185], v[56:59]
	v_mfma_f32_16x16x32_bf16 v[44:47], v[150:153], v[190:193], v[44:47]
	v_mfma_f32_16x16x32_bf16 v[40:43], v[158:161], v[190:193], v[40:43]
	v_mfma_f32_16x16x32_bf16 v[28:31], v[150:153], v[198:201], v[28:31]
	v_mfma_f32_16x16x32_bf16 v[24:27], v[158:161], v[198:201], v[24:27]
	v_mfma_f32_16x16x32_bf16 v[12:15], v[150:153], v[212:215], v[12:15]
	v_mfma_f32_16x16x32_bf16 v[8:11], v[158:161], v[212:215], v[8:11]
	v_mfma_f32_16x16x32_bf16 v[52:55], v[162:165], v[178:181], v[52:55]
	v_mfma_f32_16x16x32_bf16 v[48:51], v[170:173], v[178:181], v[48:51]
	v_mfma_f32_16x16x32_bf16 v[36:39], v[162:165], v[186:189], v[36:39]
	v_mfma_f32_16x16x32_bf16 v[32:35], v[170:173], v[186:189], v[32:35]
	v_mfma_f32_16x16x32_bf16 v[20:23], v[162:165], v[194:197], v[20:23]
	v_mfma_f32_16x16x32_bf16 v[16:19], v[170:173], v[194:197], v[16:19]
	v_mfma_f32_16x16x32_bf16 v[4:7], v[162:165], v[208:211], v[4:7]
	v_mfma_f32_16x16x32_bf16 v[0:3], v[170:173], v[208:211], v[0:3]
	v_mfma_f32_16x16x32_bf16 v[52:55], v[166:169], v[182:185], v[52:55]
	v_mfma_f32_16x16x32_bf16 v[48:51], v[174:177], v[182:185], v[48:51]
	v_mfma_f32_16x16x32_bf16 v[36:39], v[166:169], v[190:193], v[36:39]
	v_mfma_f32_16x16x32_bf16 v[32:35], v[174:177], v[190:193], v[32:35]
	v_mfma_f32_16x16x32_bf16 v[20:23], v[166:169], v[198:201], v[20:23]
	v_mfma_f32_16x16x32_bf16 v[16:19], v[174:177], v[198:201], v[16:19]
	v_mfma_f32_16x16x32_bf16 v[4:7], v[166:169], v[212:215], v[4:7]
	v_mfma_f32_16x16x32_bf16 v[0:3], v[174:177], v[212:215], v[0:3]
	s_barrier
	ds_read_b128 v[146:149], v144
	ds_read_b128 v[150:153], v144 offset:1024
	ds_read_b128 v[154:157], v144 offset:2048
	ds_read_b128 v[158:161], v144 offset:3072
	ds_read_b128 v[162:165], v145
	ds_read_b128 v[166:169], v145 offset:1024
	ds_read_b128 v[170:173], v145 offset:2048
	ds_read_b128 v[174:177], v145 offset:3072
	s_add_u32 s38, s38, 0x2b4000
	s_addc_u32 s39, s39, 0
	s_mov_b32 m0, s22
	v_lshl_add_u64 v[222:223], s[38:39], 0, v[128:129]
	ds_read_b128 v[178:181], v143 offset:32768
	ds_read_b128 v[182:185], v143 offset:33792
	ds_read_b128 v[186:189], v143 offset:34816
	ds_read_b128 v[190:193], v143 offset:35840
	ds_read_b128 v[194:197], v143 offset:36864
	ds_read_b128 v[198:201], v143 offset:37888
	ds_read_b128 v[208:211], v143 offset:38912
	ds_read_b128 v[212:215], v143 offset:39936
	global_load_lds_dwordx4 v[222:223], off
	v_lshl_add_u64 v[222:223], s[38:39], 0, v[132:133]
	s_mov_b32 m0, s23
	s_nop 0
	global_load_lds_dwordx4 v[222:223], off
	s_nop 0
	s_waitcnt vmcnt(8)
	s_waitcnt lgkmcnt(0)
	s_barrier
	s_waitcnt lgkmcnt(0)
	v_mfma_f32_16x16x32_bf16 v[124:127], v[146:149], v[178:181], v[124:127]
	v_mfma_f32_16x16x32_bf16 v[120:123], v[154:157], v[178:181], v[120:123]
	v_mfma_f32_16x16x32_bf16 v[108:111], v[146:149], v[186:189], v[108:111]
	v_mfma_f32_16x16x32_bf16 v[104:107], v[154:157], v[186:189], v[104:107]
	v_mfma_f32_16x16x32_bf16 v[92:95], v[146:149], v[194:197], v[92:95]
	v_mfma_f32_16x16x32_bf16 v[88:91], v[154:157], v[194:197], v[88:91]
	v_mfma_f32_16x16x32_bf16 v[76:79], v[146:149], v[208:211], v[76:79]
	v_mfma_f32_16x16x32_bf16 v[72:75], v[154:157], v[208:211], v[72:75]
	v_mfma_f32_16x16x32_bf16 v[124:127], v[150:153], v[182:185], v[124:127]
	v_mfma_f32_16x16x32_bf16 v[120:123], v[158:161], v[182:185], v[120:123]
	v_mfma_f32_16x16x32_bf16 v[108:111], v[150:153], v[190:193], v[108:111]
	v_mfma_f32_16x16x32_bf16 v[104:107], v[158:161], v[190:193], v[104:107]
	v_mfma_f32_16x16x32_bf16 v[92:95], v[150:153], v[198:201], v[92:95]
	v_mfma_f32_16x16x32_bf16 v[88:91], v[158:161], v[198:201], v[88:91]
	v_mfma_f32_16x16x32_bf16 v[76:79], v[150:153], v[212:215], v[76:79]
	v_mfma_f32_16x16x32_bf16 v[72:75], v[158:161], v[212:215], v[72:75]
	v_mfma_f32_16x16x32_bf16 v[116:119], v[162:165], v[178:181], v[116:119]
	v_mfma_f32_16x16x32_bf16 v[112:115], v[170:173], v[178:181], v[112:115]
	v_mfma_f32_16x16x32_bf16 v[100:103], v[162:165], v[186:189], v[100:103]
	v_mfma_f32_16x16x32_bf16 v[96:99], v[170:173], v[186:189], v[96:99]
	v_mfma_f32_16x16x32_bf16 v[84:87], v[162:165], v[194:197], v[84:87]
	v_mfma_f32_16x16x32_bf16 v[80:83], v[170:173], v[194:197], v[80:83]
	v_mfma_f32_16x16x32_bf16 v[68:71], v[162:165], v[208:211], v[68:71]
	v_mfma_f32_16x16x32_bf16 v[64:67], v[170:173], v[208:211], v[64:67]
	v_mfma_f32_16x16x32_bf16 v[116:119], v[166:169], v[182:185], v[116:119]
	v_mfma_f32_16x16x32_bf16 v[112:115], v[174:177], v[182:185], v[112:115]
	v_mfma_f32_16x16x32_bf16 v[100:103], v[166:169], v[190:193], v[100:103]
	v_mfma_f32_16x16x32_bf16 v[96:99], v[174:177], v[190:193], v[96:99]
	v_mfma_f32_16x16x32_bf16 v[84:87], v[166:169], v[198:201], v[84:87]
	v_mfma_f32_16x16x32_bf16 v[80:83], v[174:177], v[198:201], v[80:83]
	v_mfma_f32_16x16x32_bf16 v[68:71], v[166:169], v[212:215], v[68:71]
	v_mfma_f32_16x16x32_bf16 v[64:67], v[174:177], v[212:215], v[64:67]
	s_barrier
; #define PG8_STAGE(bufoff, gbase, voff) do { _Pragma("unroll") for (int _i = 0; _i < 2; ++_i) \
;         __builtin_amdgcn_global_load_lds((const unsigned*)((const char*)(gbase) + (voff)[_i]), (PG8_LAS unsigned*)(lds + (bufoff) + ldsw + _i * 8192), 16, 0, 0); } while (0)
; #define PG8_STAGE_NT(bufoff, gbase, voff) do { _Pragma("unroll") for (int _i = 0; _i < 2; ++_i) \
;         __builtin_amdgcn_global_load_lds((const unsigned*)((const char*)(gbase) + (voff)[_i]), (PG8_LAS unsigned*)(lds + (bufoff) + ldsw + _i * 8192), 16, 0, PG8_B_AUX); } while (0)
; #define PG8_LDA(dst, b, h) do { _Pragma("unroll") for (int m = 0; m < 4; ++m) _Pragma("unroll") for (int k = 0; k < 2; ++k) dst[m][k] = *(const PG8_LAS bf16x8*)(lds + PG8_SA(b, h) + aoff + m * 2048 + k * 1024); } while (0)
; #define PG8_MMA(ai, bj, At, Bt) do { __builtin_amdgcn_s_setprio(1); _Pragma("unroll") for (int m = 0; m < 4; ++m) _Pragma("unroll") for (int n = 0; n < 2; ++n) _Pragma("unroll") for (int k = 0; k < 2; ++k) \
;         acc[ai][bj][m][n] = __builtin_amdgcn_mfma_f32_16x16x32_bf16(Bt[n][k], At[m][k], acc[ai][bj][m][n], 0, 0, 0); __builtin_amdgcn_s_setprio(0); } while (0)
; #define PG8_WAIT_V(n) asm volatile("s_waitcnt vmcnt(" #n ")" ::: "memory")
; #define PG8_WAIT_L(n) asm volatile("s_waitcnt lgkmcnt(" #n ")" ::: "memory")
; #define PG8_BAR __builtin_amdgcn_s_barrier()
; #define PG8_SCHED __builtin_amdgcn_sched_barrier(0)
; template <class Epi, class Sched, bool ALIGN_EPI = false, bool SP2 = false>
; __device__ __forceinline__ void gemm_phase(PG8_LAS unsigned char* lds, const Gemm g, const Sched& S, const Epi& E, int wid) {
;     ...
;             PG8_LDA(At, 1, 1); PG8_STAGE_NT(PG8_SB(1, 0), b3, voffB); PG8_STAGE_NT(PG8_SB(1, 1), b3 + hstepB, voffB); PG8_STAGE(PG8_SA(1, 0), a3, voffA);
;             PG8_WAIT_V(8); PG8_WAIT_L(0); PG8_BAR; PG8_MMA(1, 0, At, B0); PG8_MMA(1, 1, At, B1); PG8_BAR; PG8_SCHED;
;     ...
;     PG8_WAIT_V(0);
;     if constexpr (!ALIGN_EPI) { if (wr == 0) PG8_BAR; }
;     PG8_BAR;
	s_mov_b32 m0, s63
	v_lshl_add_u64 v[202:203], v[202:203], 0, s[4:5]
	s_add_u32 s30, s30, 0x2b4080
	ds_read_b128 v[178:181], v143 offset:49152
	ds_read_b128 v[182:185], v143 offset:50176
	ds_read_b128 v[186:189], v143 offset:51200
	ds_read_b128 v[190:193], v143 offset:52224
	ds_read_b128 v[194:197], v143 offset:53248
	ds_read_b128 v[198:201], v143 offset:54272
	ds_read_b128 v[208:211], v143 offset:55296
	ds_read_b128 v[212:215], v143 offset:56320
	global_load_lds_dwordx4 v[202:203], off
	v_lshl_add_u64 v[202:203], v[216:217], 0, s[4:5]
	s_mov_b32 m0, s64
	s_addc_u32 s31, s31, 0
	global_load_lds_dwordx4 v[202:203], off
	v_lshl_add_u64 v[202:203], s[30:31], 0, v[130:131]
	s_mov_b32 m0, s65
	s_nop 0
	global_load_lds_dwordx4 v[202:203], off
	v_lshl_add_u64 v[202:203], s[30:31], 0, v[134:135]
	s_mov_b32 m0, s66
	s_nop 0
	global_load_lds_dwordx4 v[202:203], off
	v_lshl_add_u64 v[202:203], v[218:219], 0, s[4:5]
	s_mov_b32 m0, s25
	s_nop 0
	global_load_lds_dwordx4 v[202:203], off
	v_lshl_add_u64 v[202:203], v[220:221], 0, s[4:5]
	s_mov_b32 m0, s56
	s_nop 0
	global_load_lds_dwordx4 v[202:203], off
	s_waitcnt vmcnt(8)
	s_waitcnt lgkmcnt(0)
	s_barrier
	s_waitcnt lgkmcnt(0)
	v_mfma_f32_16x16x32_bf16 v[60:63], v[146:149], v[178:181], v[60:63]
	v_mfma_f32_16x16x32_bf16 v[56:59], v[154:157], v[178:181], v[56:59]
	v_mfma_f32_16x16x32_bf16 v[44:47], v[146:149], v[186:189], v[44:47]
	v_mfma_f32_16x16x32_bf16 v[40:43], v[154:157], v[186:189], v[40:43]
	v_mfma_f32_16x16x32_bf16 v[28:31], v[146:149], v[194:197], v[28:31]
	v_mfma_f32_16x16x32_bf16 v[24:27], v[154:157], v[194:197], v[24:27]
	v_mfma_f32_16x16x32_bf16 v[12:15], v[146:149], v[208:211], v[12:15]
	v_mfma_f32_16x16x32_bf16 v[8:11], v[154:157], v[208:211], v[8:11]
	v_mfma_f32_16x16x32_bf16 v[60:63], v[150:153], v[182:185], v[60:63]
	v_mfma_f32_16x16x32_bf16 v[56:59], v[158:161], v[182:185], v[56:59]
	v_mfma_f32_16x16x32_bf16 v[44:47], v[150:153], v[190:193], v[44:47]
	v_mfma_f32_16x16x32_bf16 v[40:43], v[158:161], v[190:193], v[40:43]
	v_mfma_f32_16x16x32_bf16 v[28:31], v[150:153], v[198:201], v[28:31]
	v_mfma_f32_16x16x32_bf16 v[24:27], v[158:161], v[198:201], v[24:27]
	v_mfma_f32_16x16x32_bf16 v[12:15], v[150:153], v[212:215], v[12:15]
	v_mfma_f32_16x16x32_bf16 v[8:11], v[158:161], v[212:215], v[8:11]
	v_mfma_f32_16x16x32_bf16 v[52:55], v[162:165], v[178:181], v[52:55]
	v_mfma_f32_16x16x32_bf16 v[48:51], v[170:173], v[178:181], v[48:51]
	v_mfma_f32_16x16x32_bf16 v[36:39], v[162:165], v[186:189], v[36:39]
	v_mfma_f32_16x16x32_bf16 v[32:35], v[170:173], v[186:189], v[32:35]
	v_mfma_f32_16x16x32_bf16 v[20:23], v[162:165], v[194:197], v[20:23]
	v_mfma_f32_16x16x32_bf16 v[16:19], v[170:173], v[194:197], v[16:19]
	v_mfma_f32_16x16x32_bf16 v[4:7], v[162:165], v[208:211], v[4:7]
	v_mfma_f32_16x16x32_bf16 v[0:3], v[170:173], v[208:211], v[0:3]
	v_mfma_f32_16x16x32_bf16 v[52:55], v[166:169], v[182:185], v[52:55]
	v_mfma_f32_16x16x32_bf16 v[48:51], v[174:177], v[182:185], v[48:51]
	v_mfma_f32_16x16x32_bf16 v[36:39], v[166:169], v[190:193], v[36:39]
	v_mfma_f32_16x16x32_bf16 v[32:35], v[174:177], v[190:193], v[32:35]
	v_mfma_f32_16x16x32_bf16 v[20:23], v[166:169], v[198:201], v[20:23]
	v_mfma_f32_16x16x32_bf16 v[16:19], v[174:177], v[198:201], v[16:19]
	v_mfma_f32_16x16x32_bf16 v[4:7], v[166:169], v[212:215], v[4:7]
	v_mfma_f32_16x16x32_bf16 v[0:3], v[174:177], v[212:215], v[0:3]
	s_barrier
	s_add_i32 s41, s41, 2
	s_add_u32 s21, s21, 0x100
	s_addc_u32 s40, s40, 0
	s_add_u32 s8, s8, 0x100
	s_addc_u32 s9, s9, 0
	v_lshl_add_u64 v[136:137], v[136:137], 0, s[28:29]
	s_cmpk_lt_u32 s41, 0xaa
	v_lshl_add_u64 v[138:139], v[138:139], 0, s[28:29]
	s_cbranch_scc1 .LBB0_1307
	s_waitcnt vmcnt(0)
	s_andn2_b64 vcc, exec, s[44:45]
	s_cbranch_vccnz .LBB0_1310
	s_barrier
